# code placement: all four K-loop heads on 64-byte boundaries (s_nop fill)
# speedup vs baseline: 1.0011x; 1.0011x over previous
.LBB0_131:
	s_ashr_i32 s15, s14, 31
	s_lshl_b64 s[2:3], s[14:15], 19
	s_add_u32 s16, s0, s2
	s_addc_u32 s17, s1, s3
	s_and_b64 s[2:3], s[4:5], exec
	s_cselect_b32 s15, s17, s23
	s_cselect_b32 s37, s16, s22
	s_ashr_i32 s13, s12, 31
	s_lshl_b64 s[2:3], s[12:13], 19
	v_readlane_b32 s18, v255, 31
	v_readlane_b32 s19, v255, 32
	s_add_u32 s18, s18, s2
	s_addc_u32 s19, s19, s3
	s_and_b64 s[2:3], s[4:5], exec
	s_cselect_b32 s13, s19, s7
	s_cselect_b32 s38, s18, s6
	s_add_u32 s39, s6, 0x100
	s_addc_u32 s40, s7, 0
	s_add_u32 s6, s22, 0x40080
	s_addc_u32 s7, s23, 0
	s_mov_b32 s22, -2
	.p2alignl 6, 3212836864

.LBB0_762:
	s_ashr_i32 s17, s16, 31
	s_lshl_b64 s[2:3], s[16:17], 19
	s_add_u32 s24, s4, s2
	s_addc_u32 s25, s5, s3
	s_and_b64 s[0:1], s[0:1], exec
	s_cselect_b32 s17, s25, s7
	s_cselect_b32 s40, s24, s6
	s_add_u32 s41, s6, 0x100
	s_addc_u32 s56, s7, 0
	s_mov_b32 s57, -2
	.p2alignl 6, 3212836864

.LBB0_861:
	s_ashr_i32 s17, s16, 31
	s_lshl_b64 s[2:3], s[16:17], 19
	s_add_u32 s18, s0, s2
	s_addc_u32 s19, s1, s3
	s_and_b64 s[2:3], s[8:9], exec
	s_cselect_b32 s17, s19, s7
	s_cselect_b32 s39, s18, s6
	s_ashr_i32 s15, s14, 31
	s_lshl_b64 s[2:3], s[14:15], 19
	s_add_u32 s24, s4, s2
	s_addc_u32 s25, s5, s3
	s_and_b64 s[2:3], s[8:9], exec
	s_cselect_b32 s15, s25, s23
	s_cselect_b32 s40, s24, s22
	s_add_u32 s22, s22, 0x100
	s_addc_u32 s23, s23, 0
	s_add_u32 s6, s6, 0x40080
	s_addc_u32 s7, s7, 0
	s_mov_b32 s41, -2
	.p2alignl 6, 3212836864

.LBB0_1061:
	s_add_u32 s39, s18, 0x100
	s_addc_u32 s40, s19, 0
	s_mov_b32 s41, -2
	.p2alignl 6, 3212836864
